# attention K/V DMA: workspace base folded into scalar address pairs, LDS destinations per ITER in two SGPRs, compact DMA blocks; PV waits one per pair of V fragments
# speedup vs baseline: 1.0240x; 1.0068x over previous
.Ltb_u1_b:
	s_ashr_i32 s11, s6, 6
	s_lshl_b32 s10, s43, 4
	s_lshl_b32 s26, s11, 2
	v_bfe_u32 v233, v237, 4, 2
	s_and_b32 s60, s10, 0xfffff000
	v_or_b32_e32 v52, s26, v233
	s_waitcnt vmcnt(0)
	v_add_u32_e32 v2, s60, v52
	v_ashrrev_i32_e32 v3, 31, v2
	v_readlane_b32 s18, v252, 31
	v_bitop3_b32 v0, s26, v237, v233 bitop3:0x36
	v_lshlrev_b64 v[2:3], 12, v[2:3]
	v_readlane_b32 s19, v252, 32
	s_and_b32 s46, s43, 15
	s_lshl_b32 s84, s28, 8
	v_lshl_add_u64 v[2:3], s[18:19], 0, v[2:3]
	v_lshlrev_b32_e32 v0, 4, v0
	s_xor_b32 s17, s46, 31
	s_and_b32 s2, s11, 3
	v_lshl_add_u64 v[2:3], v[2:3], 0, s[84:85]
	v_and_b32_e32 v0, 0xf0, v0
	s_lshl_b32 s27, s11, 3
	v_bfe_u32 v53, v237, 3, 3
	s_lshl_b32 s21, s17, 7
	s_lshl_b32 s22, s2, 5
	s_lshl_b32 s18, s28, 7
	v_lshl_add_u64 v[2:3], v[2:3], 0, v[0:1]
	v_or_b32_e32 v0, s27, v53
	s_or_b32 s20, s22, s21
	v_lshrrev_b32_e32 v54, 1, v0
	v_add_u32_e32 v4, s18, v0
	v_and_b32_e32 v235, 31, v237
	v_xor_b32_e32 v6, v54, v237
	v_ashrrev_i32_e32 v5, 31, v4
	v_readlane_b32 s36, v252, 39
	s_or_b32 s10, s20, s60
	v_lshlrev_b64 v[4:5], 15, v[4:5]
	v_readlane_b32 s37, v252, 40
	v_lshlrev_b32_e32 v0, 4, v6
	v_or_b32_e32 v6, s10, v235
	v_lshl_add_u64 v[4:5], s[36:37], 0, v[4:5]
	v_ashrrev_i32_e32 v7, 31, v6
	v_readlane_b32 s36, v252, 17
	s_ashr_i32 s3, s6, 8
	v_lshlrev_b64 v[6:7], 12, v[6:7]
	v_readlane_b32 s37, v252, 18
	s_ashr_i32 s61, s60, 31
	v_bfe_u32 v234, v237, 5, 1
	v_lshl_add_u64 v[6:7], s[36:37], 0, v[6:7]
	s_lshl_b32 s36, s3, 6
	v_lshl_add_u64 v[4:5], s[60:61], 1, v[4:5]
	v_and_b32_e32 v0, 0x70, v0
	v_lshl_add_u64 v[6:7], v[6:7], 0, s[84:85]
	s_ashr_i32 s37, s36, 31
	v_lshl_add_u64 v[4:5], v[4:5], 0, v[0:1]
	v_lshl_add_u64 v[6:7], s[36:37], 1, v[6:7]
	v_lshlrev_b32_e32 v0, 4, v234
	v_lshl_add_u64 v[6:7], v[6:7], 0, v[0:1]
	global_load_dwordx4 v[146:149], v[6:7], off nt
	global_load_dwordx4 v[150:153], v[6:7], off offset:32 nt
	global_load_dwordx4 v[154:157], v[6:7], off offset:64 nt
	global_load_dwordx4 v[158:161], v[6:7], off offset:96 nt
	s_lshl_b32 s11, s11, 10
	s_add_i32 s11, s11, 0
	s_mov_b32 m0, s11
	s_mov_b64 s[36:37], 0x20000
	global_load_lds_dwordx4 v[2:3], off
	v_lshl_add_u64 v[8:9], v[2:3], 0, s[36:37]
	s_add_i32 m0, s11, 0x2000
	s_mov_b64 s[36:37], 0x40000
	global_load_lds_dwordx4 v[8:9], off
	s_add_i32 m0, s11, 0x4000
	v_lshl_add_u64 v[8:9], v[2:3], 0, s[36:37]
	s_mov_b64 s[36:37], 0x60000
	global_load_lds_dwordx4 v[8:9], off
	v_lshl_add_u64 v[8:9], v[2:3], 0, s[36:37]
	s_add_i32 m0, s11, 0x6000
	s_mov_b64 s[36:37], 0x200000
	global_load_lds_dwordx4 v[8:9], off
	s_add_i32 m0, s11, 0xc000
	v_lshl_add_u64 v[8:9], v[4:5], 0, s[36:37]
	global_load_lds_dwordx4 v[4:5], off
	s_add_i32 m0, s11, 0xe000
	s_mov_b64 s[36:37], 0xa0000
	global_load_lds_dwordx4 v[8:9], off
	s_add_i32 m0, s11, 0x8000
	v_lshl_add_u64 v[8:9], v[2:3], 0, s[34:35]
	global_load_lds_dwordx4 v[8:9], off
	v_lshl_add_u64 v[2:3], v[2:3], 0, s[36:37]
	s_add_i32 m0, s11, 0xa000
	s_mov_b64 s[36:37], 0x80
	global_load_lds_dwordx4 v[2:3], off
	s_add_i32 m0, s11, 0x10000
	v_lshl_add_u64 v[2:3], v[4:5], 0, s[36:37]
	s_mov_b64 s[36:37], 0x200080
	global_load_lds_dwordx4 v[2:3], off
	v_lshl_add_u64 v[2:3], v[4:5], 0, s[36:37]
	s_add_i32 m0, s11, 0x12000
	v_and_b32_e32 v0, 19, v237
	global_load_lds_dwordx4 v[2:3], off
	v_lshlrev_b32_e32 v2, 1, v237
	v_lshrrev_b32_e32 v35, 1, v34
	v_and_or_b32 v0, v2, 8, v0
	v_and_b32_e32 v22, 4, v35
	v_or_b32_e32 v2, v0, v22
	v_lshl_or_b32 v45, s3, 3, v234
	v_lshlrev_b32_e32 v44, 8, v2
	v_bitop3_b32 v2, v2, v45, 15 bitop3:0x6c
	v_lshl_add_u32 v239, v2, 4, v44
	s_waitcnt vmcnt(4)
	s_barrier
	v_add_u32_e32 v6, 0, v239
	v_bitop3_b32 v0, v0, 15, v22 bitop3:0xc8
	ds_read_b128 v[2:5], v6
	ds_read_b128 v[18:21], v6 offset:8192
	v_bitop3_b32 v22, v45, v0, 2 bitop3:0x36
	v_lshl_add_u32 v240, v22, 4, v44
	v_add_u32_e32 v40, 0, v240
	ds_read_b128 v[36:39], v40
	s_waitcnt vmcnt(0) lgkmcnt(0)
	v_mfma_f32_32x32x16_bf16 v[2:17], v[2:5], v[146:149], 0
	ds_read_b128 v[40:43], v40 offset:8192
	v_bfe_u32 v34, v34, 1, 3
	v_bitop3_b32 v57, v234, v34, 2 bitop3:0x36
	v_bitop3_b32 v58, v234, v34, 4 bitop3:0x36
	v_bitop3_b32 v59, v234, v34, 6 bitop3:0x36
	s_and_b32 s56, s42, 0xfffff000
	s_add_i32 s26, s26, s56
	v_mfma_f32_32x32x16_bf16 v[18:33], v[18:21], v[146:149], 0
	s_lshr_b32 s16, s43, 4
	s_and_b32 s16, s16, 15
	s_lshl_b32 s36, s16, 7
	s_lshl_b32 s37, s16, 8
	s_add_i32 s27, s27, s36
	s_ashr_i32 s57, s56, 31
	s_lshl_b64 s[44:45], s[56:57], 1
	v_mfma_f32_32x32x16_bf16 v[2:17], v[36:39], v[150:153], v[2:17]
	v_bitop3_b32 v36, v45, v0, 4 bitop3:0x36
	v_lshl_add_u32 v241, v36, 4, v44
	v_add_u32_e32 v46, 0, v241
	ds_read_b128 v[36:39], v46
	v_bitop3_b32 v0, v45, v0, 6 bitop3:0x36
	v_lshl_add_u32 v243, v0, 4, v44
	v_add_u32_e32 v0, 0, v243
	s_waitcnt lgkmcnt(1)
	v_mfma_f32_32x32x16_bf16 v[18:33], v[40:43], v[150:153], v[18:33]
	ds_read_b128 v[40:43], v46 offset:8192
	v_lshlrev_b32_e32 v236, 3, v234
	s_mov_b32 s84, s85
	v_bitop3_b32 v56, v35, v234, 7 bitop3:0x6c
	s_mov_b32 s86, s85
	s_mov_b32 s87, s85
	s_mov_b32 s88, s85
	s_waitcnt lgkmcnt(1)
	v_mfma_f32_32x32x16_bf16 v[2:17], v[36:39], v[154:157], v[2:17]
	ds_read_b128 v[36:39], v0
	s_mov_b32 s89, s85
	s_mov_b32 s90, s85
	s_mov_b32 s91, s85
	s_mov_b32 s92, s85
	s_mov_b32 s93, s85
	s_mov_b32 s94, s85
	s_waitcnt lgkmcnt(1)
	v_mfma_f32_32x32x16_bf16 v[18:33], v[40:43], v[154:157], v[18:33]
	ds_read_b128 v[40:43], v0 offset:8192
	s_mov_b32 s95, s85
	s_mov_b32 s96, s85
	s_mov_b32 s97, s85
	s_mov_b32 s98, s85
	s_mov_b32 s99, s85
	s_lshl_b32 s16, s17, 1
	s_waitcnt lgkmcnt(1)
	v_mfma_f32_32x32x16_bf16 v[2:17], v[36:39], v[158:161], v[2:17]
	v_lshlrev_b32_e32 v55, 7, v235
	s_lshr_b32 s19, s20, 6
	s_add_i32 s17, s16, 2
	s_add_i32 s19, s19, 1
	v_lshl_or_b32 v244, v56, 4, v55
	v_lshl_or_b32 v245, v57, 4, v55
	v_lshl_or_b32 v246, v58, 4, v55
	s_waitcnt lgkmcnt(0)
	v_mfma_f32_32x32x16_bf16 v[18:33], v[40:43], v[158:161], v[18:33]
	s_nop 2
	v_max_f32_e32 v34, v3, v3
	v_lshl_or_b32 v247, v59, 4, v55
	s_mov_b32 s23, 1
	v_and_b32_e32 v238, 63, v237
	s_mov_b32 s31, 2
	s_min_u32 s19, s17, s19
	s_addk_i32 s20, 0xff50
	s_nop 1
	v_max_f32_e32 v0, v19, v19
	v_max_f32_e32 v0, v34, v0
	v_max3_f32 v0, v2, v18, v0
	v_max3_f32 v34, v20, v5, v21
	v_max3_f32 v0, v0, v4, v34
	v_max3_f32 v34, v22, v7, v23
	v_max3_f32 v0, v0, v6, v34
	v_max3_f32 v34, v24, v9, v25
	v_max3_f32 v0, v0, v8, v34
	v_max3_f32 v34, v26, v11, v27
	v_max3_f32 v0, v0, v10, v34
	v_max3_f32 v34, v28, v13, v29
	v_max3_f32 v0, v0, v12, v34
	v_max3_f32 v34, v30, v15, v31
	v_max3_f32 v0, v0, v14, v34
	v_max3_f32 v34, v32, v17, v33
	v_max3_f32 v0, v0, v16, v34
	v_mov_b32_e32 v34, v0
	s_nop 1
	v_permlane32_swap_b32_e32 v0, v34
	v_max_f32_e32 v34, v34, v34
	v_max_f32_e32 v0, v0, v0
	v_max_f32_e32 v213, v0, v34
	v_sub_f32_e32 v0, v2, v213
	v_exp_f32_e32 v60, v0
	v_sub_f32_e32 v0, v18, v213
	v_exp_f32_e32 v61, v0
	v_sub_f32_e32 v0, v3, v213
	v_sub_f32_e32 v2, v19, v213
	v_exp_f32_e32 v0, v0
	v_exp_f32_e32 v2, v2
	v_add_f32_e32 v3, v61, v60
	v_mov_b64_e32 v[34:35], s[84:85]
	v_cvt_pk_bf16_f32 v162, v60, v0
	v_pk_add_f32 v[18:19], v[2:3], v[0:1]
	v_sub_f32_e32 v3, v4, v213
	v_sub_f32_e32 v4, v20, v213
	v_pk_add_f32 v[18:19], v[18:19], v[18:19] op_sel_hi:[0,1]
	v_exp_f32_e32 v62, v4
	v_sub_f32_e32 v4, v5, v213
	v_exp_f32_e32 v3, v3
	v_exp_f32_e32 v18, v4
	v_sub_f32_e32 v4, v21, v213
	v_exp_f32_e32 v4, v4
	v_add_f32_e32 v5, v62, v3
	v_sub_u32_e32 v0, 7, v237
	v_cvt_pk_bf16_f32 v178, v61, v2
	v_pk_add_f32 v[20:21], v[4:5], v[18:19]
	v_sub_f32_e32 v5, v6, v213
	v_sub_f32_e32 v6, v22, v213
	v_pk_add_f32 v[20:21], v[20:21], v[20:21] op_sel_hi:[0,1]
	v_exp_f32_e32 v19, v6
	v_sub_f32_e32 v6, v7, v213
	v_exp_f32_e32 v5, v5
	v_exp_f32_e32 v20, v6
	v_sub_f32_e32 v6, v23, v213
	v_exp_f32_e32 v6, v6
	v_add_f32_e32 v7, v19, v5
	v_and_b32_e32 v0, 3, v0
	v_mov_b32_e32 v2, s33
	v_pk_add_f32 v[22:23], v[6:7], v[20:21]
	v_sub_f32_e32 v7, v8, v213
	v_sub_f32_e32 v8, v24, v213
	v_pk_add_f32 v[22:23], v[22:23], v[22:23] op_sel_hi:[0,1]
	v_exp_f32_e32 v21, v8
	v_sub_f32_e32 v8, v9, v213
	v_exp_f32_e32 v7, v7
	v_exp_f32_e32 v22, v8
	v_sub_f32_e32 v8, v25, v213
	v_exp_f32_e32 v8, v8
	v_add_f32_e32 v9, v21, v7
	s_movk_i32 s33, 0x510
	v_mad_u32_u24 v0, v0, s33, v2
	v_pk_add_f32 v[24:25], v[8:9], v[22:23]
	v_sub_f32_e32 v9, v10, v213
	v_sub_f32_e32 v10, v26, v213
	v_pk_add_f32 v[24:25], v[24:25], v[24:25] op_sel_hi:[0,1]
	v_exp_f32_e32 v23, v10
	v_sub_f32_e32 v10, v11, v213
	v_exp_f32_e32 v9, v9
	v_exp_f32_e32 v24, v10
	v_sub_f32_e32 v10, v27, v213
	v_exp_f32_e32 v10, v10
	v_add_f32_e32 v11, v23, v9
	v_or_b32_e32 v2, s26, v233
	v_cvt_pk_bf16_f32 v163, v3, v18
	v_pk_add_f32 v[26:27], v[10:11], v[24:25]
	v_sub_f32_e32 v11, v12, v213
	v_sub_f32_e32 v12, v28, v213
	v_pk_add_f32 v[26:27], v[26:27], v[26:27] op_sel_hi:[0,1]
	v_exp_f32_e32 v25, v12
	v_sub_f32_e32 v12, v13, v213
	v_exp_f32_e32 v11, v11
	v_exp_f32_e32 v26, v12
	v_sub_f32_e32 v12, v29, v213
	v_exp_f32_e32 v12, v12
	v_add_f32_e32 v13, v25, v11
	v_ashrrev_i32_e32 v3, 31, v2
	v_lshlrev_b64 v[214:215], 12, v[2:3]
	v_pk_add_f32 v[28:29], v[12:13], v[26:27]
	v_sub_f32_e32 v13, v14, v213
	v_sub_f32_e32 v14, v30, v213
	v_pk_add_f32 v[28:29], v[28:29], v[28:29] op_sel_hi:[0,1]
	v_exp_f32_e32 v27, v14
	v_sub_f32_e32 v14, v15, v213
	v_exp_f32_e32 v13, v13
	v_exp_f32_e32 v28, v14
	v_sub_f32_e32 v14, v31, v213
	v_exp_f32_e32 v14, v14
	v_sub_f32_e32 v15, v16, v213
	v_exp_f32_e32 v63, v15
	v_sub_f32_e32 v15, v32, v213
	v_exp_f32_e32 v32, v15
	v_add_f32_e32 v15, v27, v13
	v_pk_add_f32 v[30:31], v[14:15], v[28:29]
	v_bitop3_b32 v2, v52, 15, v237 bitop3:0x48
	v_pk_add_f32 v[30:31], v[30:31], v[30:31] op_sel_hi:[0,1]
	v_sub_f32_e32 v15, v17, v213
	v_lshlrev_b32_e32 v2, 4, v2
	v_exp_f32_e32 v30, v15
	v_sub_f32_e32 v15, v33, v213
	v_or3_b32 v214, v214, s37, v2
	v_or_b32_e32 v2, s27, v53
	v_exp_f32_e32 v50, v15
	v_ashrrev_i32_e32 v3, 31, v2
	v_cvt_pk_bf16_f32 v179, v62, v4
	v_lshlrev_b64 v[2:3], 15, v[2:3]
	v_bitop3_b32 v4, v54, 7, v237 bitop3:0x48
	v_lshl_or_b32 v2, v4, 4, v2
	v_add_f32_e32 v51, v32, v63
	v_lshl_add_u64 v[216:217], v[2:3], 0, s[44:45]
	v_sub_u32_e32 v2, v236, v235
	v_mov_b64_e32 v[48:49], s[98:99]
	v_pk_add_f32 v[16:17], v[50:51], v[30:31]
	v_subrev_u32_e32 v2, s22, v2
	v_mov_b64_e32 v[36:37], s[86:87]
	v_mov_b64_e32 v[38:39], s[88:89]
	v_mov_b64_e32 v[40:41], s[90:91]
	v_mov_b64_e32 v[42:43], s[92:93]
	v_mov_b64_e32 v[44:45], s[94:95]
	v_mov_b64_e32 v[46:47], s[96:97]
	v_xor_b32_e32 v66, 0x80000000, v213
	v_add_f32_e32 v242, v16, v17
	v_cvt_pk_bf16_f32 v164, v5, v20
	v_cvt_pk_bf16_f32 v165, v7, v22
	v_cvt_pk_bf16_f32 v170, v9, v24
	v_cvt_pk_bf16_f32 v171, v11, v26
	v_cvt_pk_bf16_f32 v172, v13, v28
	v_cvt_pk_bf16_f32 v173, v63, v30
	v_cvt_pk_bf16_f32 v180, v19, v6
	v_cvt_pk_bf16_f32 v181, v21, v8
	v_cvt_pk_bf16_f32 v186, v23, v10
	v_cvt_pk_bf16_f32 v187, v25, v12
	v_cvt_pk_bf16_f32 v188, v27, v14
	v_cvt_pk_bf16_f32 v189, v32, v50
	v_subrev_u32_e32 v248, s21, v2
	v_mov_b64_e32 v[64:65], v[48:49]
	v_mov_b64_e32 v[18:19], v[34:35]
	v_mov_b64_e32 v[2:3], v[34:35]
	v_readlane_b32 s94, v255, 10
	v_readlane_b32 s90, v255, 12
	v_mov_b32_e32 v67, v66
	v_mov_b32_e32 v68, v66
	v_mov_b32_e32 v69, v66
	v_mov_b32_e32 v70, v66
	v_mov_b32_e32 v71, v66
	v_mov_b32_e32 v72, v66
	v_mov_b32_e32 v73, v66
	v_mov_b32_e32 v74, v66
	v_mov_b32_e32 v75, v66
	v_mov_b32_e32 v76, v66
	v_mov_b32_e32 v77, v66
	v_mov_b32_e32 v78, v66
	v_mov_b32_e32 v79, v66
	v_mov_b32_e32 v80, v66
	v_mov_b32_e32 v81, v66
	s_mov_b32 s21, 0
	v_mov_b32_e32 v166, 0
	v_mov_b32_e32 v167, 0
	v_mov_b32_e32 v168, 0
	v_mov_b32_e32 v169, 0
	v_mov_b32_e32 v174, 0
	v_mov_b32_e32 v175, 0
	v_mov_b32_e32 v176, 0
	v_mov_b32_e32 v177, 0
	v_mov_b32_e32 v182, 0
	v_mov_b32_e32 v183, 0
	v_mov_b32_e32 v184, 0
	v_mov_b32_e32 v185, 0
	v_mov_b32_e32 v190, 0
	v_mov_b32_e32 v191, 0
	v_mov_b32_e32 v192, 0
	v_mov_b32_e32 v193, 0
	v_mov_b64_e32 v[62:63], v[46:47]
	v_mov_b64_e32 v[60:61], v[44:45]
	v_mov_b64_e32 v[58:59], v[42:43]
	v_mov_b64_e32 v[56:57], v[40:41]
	v_mov_b64_e32 v[54:55], v[38:39]
	v_mov_b64_e32 v[52:53], v[36:37]
	v_mov_b64_e32 v[50:51], v[34:35]
	v_mov_b64_e32 v[20:21], v[36:37]
	v_mov_b64_e32 v[22:23], v[38:39]
	v_mov_b64_e32 v[24:25], v[40:41]
	v_mov_b64_e32 v[26:27], v[42:43]
	v_mov_b64_e32 v[28:29], v[44:45]
	v_mov_b64_e32 v[30:31], v[46:47]
	v_mov_b64_e32 v[32:33], v[48:49]
	v_mov_b64_e32 v[4:5], v[36:37]
	v_mov_b64_e32 v[6:7], v[38:39]
	v_mov_b64_e32 v[8:9], v[40:41]
	v_mov_b64_e32 v[10:11], v[42:43]
	v_mov_b64_e32 v[12:13], v[44:45]
	v_mov_b64_e32 v[14:15], v[46:47]
	v_mov_b64_e32 v[16:17], v[48:49]
	s_mov_b32 s33, 1
	s_mov_b32 s48, 0
	s_mov_b32 s49, 0
	s_movk_i32 s92, 0x6e
	s_movk_i32 s93, 0xd0
	s_mov_b32 s57, 0x41000000
	v_readlane_b32 s95, v255, 11
	v_readlane_b32 s91, v255, 13
	s_add_u32 s80, s8, 0xd0c0000
	s_addc_u32 s81, s9, 0
	s_add_u32 s62, s8, 0xd0e0000
	s_addc_u32 s63, s9, 0
	s_add_u32 s96, s8, 0x15000100
	s_addc_u32 s97, s9, 0
	s_add_u32 s58, s8, 0x15200100
	s_addc_u32 s59, s9, 0
	s_add_u32 s50, s8, 0xd100000
	s_addc_u32 s51, s9, 0
	s_add_u32 s4, s8, 0xd120000
	s_addc_u32 s5, s9, 0
	s_add_u32 s0, s8, 0x15000180
	s_addc_u32 s1, s9, 0
	s_add_u32 s52, s8, 0x15200180
	s_addc_u32 s53, s9, 0

.LBB0_185:
	s_lshl_b32 s22, s33, 14
	s_lshl_b32 s100, s48, 14
	s_add_i32 s100, s11, s100
	s_lshl_b32 s101, s31, 14
	s_add_i32 s101, s11, s101
	ds_read_b128 v[126:129], v249 offset:49152
	s_waitcnt lgkmcnt(1)
	v_mfma_f32_32x32x16_bf16 v[82:97], v[98:101], v[146:149], v[66:81]
	ds_read_b128 v[122:125], v102 offset:8192
	v_mfma_f32_32x32x16_bf16 v[98:113], v[114:117], v[146:149], v[66:81]
	v_add_u32_e32 v139, s22, v241
	ds_read_b128 v[114:117], v139
	v_mfma_f32_32x32x16_bf16 v[82:97], v[118:121], v[150:153], v[82:97]
	ds_read_b128 v[118:121], v139 offset:8192
	s_waitcnt lgkmcnt(0)
	v_mfma_f32_32x32x16_bf16 v[98:113], v[122:125], v[150:153], v[98:113]
	v_add_u32_e32 v139, s22, v243
	ds_read_b128 v[122:125], v139
	v_mfma_f32_32x32x16_bf16 v[82:97], v[114:117], v[154:157], v[82:97]
	ds_read_b128 v[114:117], v139 offset:8192
	v_mfma_f32_32x32x16_bf16 v[98:113], v[118:121], v[154:157], v[98:113]
	s_waitcnt lgkmcnt(0)
	v_mfma_f32_32x32x16_bf16 v[82:97], v[122:125], v[158:161], v[82:97]
	v_mfma_f32_32x32x16_bf16 v[98:113], v[114:117], v[158:161], v[98:113]
	s_nop 0
	ds_read_b128 v[122:125], v249 offset:53248
	ds_read_b128 v[118:121], v249 offset:57344
	ds_read_b128 v[114:117], v249 offset:61440
	s_add_i32 s22, s21, 64
	s_cmp_le_u32 s22, s20
	s_cbranch_scc0 .Lnear_u1e
.LBB0_188:
	v_mfma_f32_32x32x16_bf16 v[34:49], v[126:129], v[162:165], v[34:49]
	ds_read_b128 v[126:129], v212 offset:49152
	s_nop 0
	v_exp_f32_e32 v130, v82
	v_exp_f32_e32 v131, v83
	v_add_f32_e32 v132, v1, v130
	v_add_f32_e32 v133, v1, v131
	v_cvt_pk_bf16_f32 v166, v130, v131
	s_waitcnt lgkmcnt(3)
	v_mfma_f32_32x32x16_bf16 v[50:65], v[122:125], v[162:165], v[50:65]
	ds_read_b128 v[122:125], v212 offset:53248
	v_exp_f32_e32 v134, v84
	v_exp_f32_e32 v135, v85
	s_add_i32 s22, s23, 2
	v_add_f32_e32 v130, v132, v134
	v_add_f32_e32 v131, v133, v135
	v_cvt_pk_bf16_f32 v167, v134, v135
	s_mov_b32 m0, s100
	s_cmp_ge_u32 s22, s17
	s_cbranch_scc1 .LBB0_190
	global_load_lds_dwordx4 v214, s[80:81]
.LBB0_190:
	s_waitcnt lgkmcnt(2)
	v_mfma_f32_32x32x16_bf16 v[18:33], v[118:121], v[162:165], v[18:33]
	ds_read_b128 v[118:121], v212 offset:57344
	v_exp_f32_e32 v132, v86
	v_exp_f32_e32 v133, v87
	v_add_f32_e32 v130, v130, v132
	v_add_f32_e32 v131, v131, v133
	v_cvt_pk_bf16_f32 v168, v132, v133
	v_mfma_f32_32x32x16_bf16 v[2:17], v[114:117], v[162:165], v[2:17]
	ds_read_b128 v[114:117], v212 offset:61440
	v_exp_f32_e32 v132, v88
	v_exp_f32_e32 v133, v89
	v_add_f32_e32 v134, v130, v132
	v_add_f32_e32 v131, v131, v133
	v_cvt_pk_bf16_f32 v169, v132, v133
	s_waitcnt lgkmcnt(2)
	v_mfma_f32_32x32x16_bf16 v[34:49], v[126:129], v[170:173], v[34:49]
	v_add_u32_e32 v130, s54, v246
	ds_read_b128 v[126:129], v130 offset:49152
	v_exp_f32_e32 v132, v90
	v_exp_f32_e32 v133, v91
	v_add_f32_e32 v134, v134, v132
	v_add_f32_e32 v135, v131, v133
	v_cvt_pk_bf16_f32 v174, v132, v133
	v_mfma_f32_32x32x16_bf16 v[50:65], v[122:125], v[170:173], v[50:65]
	ds_read_b128 v[122:125], v130 offset:53248
	v_exp_f32_e32 v133, v92
	v_exp_f32_e32 v136, v93
	v_add_f32_e32 v131, v134, v133
	v_add_f32_e32 v132, v135, v136
	s_add_i32 m0, s100, 0x2000
	s_cmp_ge_u32 s22, s17
	v_cvt_pk_bf16_f32 v175, v133, v136
	s_cbranch_scc1 .LBB0_192
	global_load_lds_dwordx4 v214, s[62:63]
.LBB0_192:
	s_waitcnt lgkmcnt(2)
	v_mfma_f32_32x32x16_bf16 v[18:33], v[118:121], v[170:173], v[18:33]
	ds_read_b128 v[118:121], v130 offset:57344
	v_exp_f32_e32 v133, v94
	v_exp_f32_e32 v134, v95
	v_add_f32_e32 v131, v131, v133
	v_add_f32_e32 v132, v132, v134
	v_cvt_pk_bf16_f32 v176, v133, v134
	v_mfma_f32_32x32x16_bf16 v[2:17], v[114:117], v[170:173], v[2:17]
	ds_read_b128 v[114:117], v130 offset:61440
	v_exp_f32_e32 v130, v96
	v_exp_f32_e32 v133, v97
	v_add_f32_e32 v131, v131, v130
	v_add_f32_e32 v132, v132, v133
	v_cvt_pk_bf16_f32 v177, v130, v133
	s_waitcnt lgkmcnt(2)
	v_mfma_f32_32x32x16_bf16 v[34:49], v[126:129], v[178:181], v[34:49]
	v_add_u32_e32 v130, s54, v247
	ds_read_b128 v[126:129], v130 offset:49152
	v_exp_f32_e32 v133, v98
	v_exp_f32_e32 v134, v99
	v_add_f32_e32 v131, v131, v133
	v_add_f32_e32 v132, v132, v134
	v_cvt_pk_bf16_f32 v182, v133, v134
	v_mfma_f32_32x32x16_bf16 v[50:65], v[122:125], v[178:181], v[50:65]
	v_exp_f32_e32 v133, v100
	v_exp_f32_e32 v134, v101
	ds_read_b128 v[122:125], v130 offset:53248
	v_add_f32_e32 v131, v131, v133
	v_add_f32_e32 v132, v132, v134
	v_cvt_pk_bf16_f32 v183, v133, v134
	s_add_i32 m0, s101, 0xc000
	s_cmp_eq_u64 s[88:89], 0
	s_cbranch_scc1 .LBB0_194
	global_load_lds_dwordx4 v216, s[96:97]
.LBB0_194:
	s_waitcnt lgkmcnt(2)
	v_mfma_f32_32x32x16_bf16 v[18:33], v[118:121], v[178:181], v[18:33]
	ds_read_b128 v[118:121], v130 offset:57344
	v_exp_f32_e32 v133, v102
	v_exp_f32_e32 v134, v103
	v_add_f32_e32 v131, v131, v133
	v_add_f32_e32 v132, v132, v134
	v_cvt_pk_bf16_f32 v184, v133, v134
	v_mfma_f32_32x32x16_bf16 v[2:17], v[114:117], v[178:181], v[2:17]
	ds_read_b128 v[114:117], v130 offset:61440
	v_exp_f32_e32 v130, v104
	v_exp_f32_e32 v133, v105
	v_add_f32_e32 v131, v131, v130
	v_add_f32_e32 v132, v132, v133
	v_cvt_pk_bf16_f32 v185, v130, v133
	s_waitcnt lgkmcnt(2)
	v_mfma_f32_32x32x16_bf16 v[34:49], v[126:129], v[186:189], v[34:49]
	v_exp_f32_e32 v126, v106
	v_exp_f32_e32 v127, v107
	v_add_f32_e32 v128, v131, v126
	v_add_f32_e32 v129, v132, v127
	v_cvt_pk_bf16_f32 v190, v126, v127
	v_mfma_f32_32x32x16_bf16 v[50:65], v[122:125], v[186:189], v[50:65]
	v_exp_f32_e32 v124, v108
	v_exp_f32_e32 v125, v109
	v_add_f32_e32 v122, v128, v124
	v_add_f32_e32 v123, v129, v125
	s_add_i32 m0, s101, 0xe000
	s_cmp_eq_u64 s[88:89], 0
	v_cvt_pk_bf16_f32 v191, v124, v125
	s_cbranch_scc1 .LBB0_196
	global_load_lds_dwordx4 v216, s[58:59]
.LBB0_196:
	s_waitcnt lgkmcnt(0)
	v_mfma_f32_32x32x16_bf16 v[18:33], v[118:121], v[186:189], v[18:33]
	v_exp_f32_e32 v118, v110
	v_exp_f32_e32 v119, v111
	v_add_f32_e32 v120, v122, v118
	v_add_f32_e32 v121, v123, v119
	v_cvt_pk_bf16_f32 v192, v118, v119
	v_mfma_f32_32x32x16_bf16 v[2:17], v[114:117], v[186:189], v[2:17]
	v_exp_f32_e32 v114, v112
	v_exp_f32_e32 v115, v113
	v_add_f32_e32 v116, v120, v114
	v_add_f32_e32 v117, v121, v115
	v_cvt_pk_bf16_f32 v193, v114, v115
	v_add_f32_e32 v212, v116, v117
	v_cmp_nge_f32_e32 vcc, s7, v212
	s_cbranch_vccnz .Lrare_u1e

.LBB0_225:
	s_lshl_b32 s26, s33, 14
	s_lshl_b32 s100, s48, 14
	s_add_i32 s100, s11, s100
	s_lshl_b32 s101, s31, 14
	s_add_i32 s101, s11, s101
	ds_read_b128 v[126:129], v249 offset:49152
	s_waitcnt lgkmcnt(1)
	v_mfma_f32_32x32x16_bf16 v[82:97], v[98:101], v[146:149], v[66:81]
	ds_read_b128 v[122:125], v102 offset:8192
	v_mfma_f32_32x32x16_bf16 v[98:113], v[114:117], v[146:149], v[66:81]
	v_add_u32_e32 v139, s26, v241
	ds_read_b128 v[114:117], v139
	v_mfma_f32_32x32x16_bf16 v[82:97], v[118:121], v[150:153], v[82:97]
	ds_read_b128 v[118:121], v139 offset:8192
	s_waitcnt lgkmcnt(0)
	v_mfma_f32_32x32x16_bf16 v[98:113], v[122:125], v[150:153], v[98:113]
	v_add_u32_e32 v139, s26, v243
	ds_read_b128 v[122:125], v139
	v_mfma_f32_32x32x16_bf16 v[82:97], v[114:117], v[154:157], v[82:97]
	ds_read_b128 v[114:117], v139 offset:8192
	v_mfma_f32_32x32x16_bf16 v[98:113], v[118:121], v[154:157], v[98:113]
	s_waitcnt lgkmcnt(0)
	v_mfma_f32_32x32x16_bf16 v[82:97], v[122:125], v[158:161], v[82:97]
	v_mfma_f32_32x32x16_bf16 v[98:113], v[114:117], v[158:161], v[98:113]
	s_nop 0
	ds_read_b128 v[122:125], v249 offset:53248
	ds_read_b128 v[118:121], v249 offset:57344
	ds_read_b128 v[114:117], v249 offset:61440
	s_add_i32 s26, s21, 0x80
	s_cmp_le_u32 s26, s20
	s_cbranch_scc0 .Lnear_u1o
.LBB0_228:
	v_mfma_f32_32x32x16_bf16 v[34:49], v[126:129], v[166:169], v[34:49]
	ds_read_b128 v[126:129], v212 offset:49152
	s_nop 0
	v_exp_f32_e32 v130, v82
	v_exp_f32_e32 v131, v83
	v_add_f32_e32 v132, v1, v130
	v_add_f32_e32 v133, v1, v131
	v_cvt_pk_bf16_f32 v162, v130, v131
	s_waitcnt lgkmcnt(3)
	v_mfma_f32_32x32x16_bf16 v[50:65], v[122:125], v[166:169], v[50:65]
	ds_read_b128 v[122:125], v212 offset:53248
	v_exp_f32_e32 v130, v84
	v_exp_f32_e32 v131, v85
	s_add_i32 s23, s23, 3
	s_cmp_le_u32 s23, s16
	v_add_f32_e32 v132, v132, v130
	v_add_f32_e32 v133, v133, v131
	v_cvt_pk_bf16_f32 v163, v130, v131
	s_cselect_b64 s[26:27], -1, 0
	s_mov_b32 m0, s100
	s_cmp_gt_u32 s23, s16
	s_cbranch_scc1 .LBB0_230
	global_load_lds_dwordx4 v214, s[50:51]
.LBB0_230:
	s_waitcnt lgkmcnt(2)
	v_mfma_f32_32x32x16_bf16 v[18:33], v[118:121], v[166:169], v[18:33]
	ds_read_b128 v[118:121], v212 offset:57344
	v_exp_f32_e32 v134, v86
	v_exp_f32_e32 v135, v87
	v_add_f32_e32 v132, v132, v134
	v_add_f32_e32 v133, v133, v135
	v_cvt_pk_bf16_f32 v164, v134, v135
	v_mfma_f32_32x32x16_bf16 v[2:17], v[114:117], v[166:169], v[2:17]
	ds_read_b128 v[114:117], v212 offset:61440
	v_exp_f32_e32 v134, v88
	v_exp_f32_e32 v135, v89
	v_add_f32_e32 v136, v132, v134
	v_add_f32_e32 v133, v133, v135
	v_cvt_pk_bf16_f32 v165, v134, v135
	s_waitcnt lgkmcnt(2)
	v_mfma_f32_32x32x16_bf16 v[34:49], v[126:129], v[174:177], v[34:49]
	v_add_u32_e32 v132, s54, v246
	ds_read_b128 v[126:129], v132 offset:49152
	v_exp_f32_e32 v134, v90
	v_exp_f32_e32 v135, v91
	v_add_f32_e32 v136, v136, v134
	v_add_f32_e32 v137, v133, v135
	v_cvt_pk_bf16_f32 v170, v134, v135
	v_mfma_f32_32x32x16_bf16 v[50:65], v[122:125], v[174:177], v[50:65]
	ds_read_b128 v[122:125], v132 offset:53248
	v_exp_f32_e32 v135, v92
	v_exp_f32_e32 v138, v93
	v_add_f32_e32 v133, v136, v135
	v_add_f32_e32 v134, v137, v138
	s_add_i32 m0, s100, 0x2000
	s_andn2_b64 vcc, exec, s[26:27]
	v_cvt_pk_bf16_f32 v171, v135, v138
	s_cbranch_vccnz .LBB0_232
	global_load_lds_dwordx4 v214, s[4:5]
.LBB0_232:
	s_waitcnt lgkmcnt(2)
	v_mfma_f32_32x32x16_bf16 v[18:33], v[118:121], v[174:177], v[18:33]
	ds_read_b128 v[118:121], v132 offset:57344
	v_exp_f32_e32 v130, v94
	v_exp_f32_e32 v131, v95
	v_add_f32_e32 v133, v133, v130
	v_add_f32_e32 v134, v134, v131
	v_cvt_pk_bf16_f32 v172, v130, v131
	v_mfma_f32_32x32x16_bf16 v[2:17], v[114:117], v[174:177], v[2:17]
	ds_read_b128 v[114:117], v132 offset:61440
	v_exp_f32_e32 v130, v96
	v_exp_f32_e32 v131, v97
	v_add_f32_e32 v133, v133, v130
	v_add_f32_e32 v134, v134, v131
	v_cvt_pk_bf16_f32 v173, v130, v131
	s_waitcnt lgkmcnt(2)
	v_mfma_f32_32x32x16_bf16 v[34:49], v[126:129], v[182:185], v[34:49]
	v_add_u32_e32 v132, s54, v247
	ds_read_b128 v[126:129], v132 offset:49152
	v_exp_f32_e32 v130, v98
	v_exp_f32_e32 v131, v99
	v_add_f32_e32 v133, v133, v130
	v_add_f32_e32 v134, v134, v131
	v_cvt_pk_bf16_f32 v178, v130, v131
	v_mfma_f32_32x32x16_bf16 v[50:65], v[122:125], v[182:185], v[50:65]
	v_exp_f32_e32 v130, v100
	v_exp_f32_e32 v131, v101
	ds_read_b128 v[122:125], v132 offset:53248
	v_add_f32_e32 v133, v133, v130
	v_add_f32_e32 v134, v134, v131
	v_cvt_pk_bf16_f32 v179, v130, v131
	s_add_i32 m0, s101, 0xc000
	s_cmp_eq_u64 s[88:89], 0
	s_cbranch_scc1 .LBB0_234
	global_load_lds_dwordx4 v216, s[0:1]
.LBB0_234:
	s_waitcnt lgkmcnt(2)
	v_mfma_f32_32x32x16_bf16 v[18:33], v[118:121], v[182:185], v[18:33]
	ds_read_b128 v[118:121], v132 offset:57344
	v_exp_f32_e32 v135, v102
	v_exp_f32_e32 v136, v103
	v_add_f32_e32 v133, v133, v135
	v_add_f32_e32 v134, v134, v136
	v_cvt_pk_bf16_f32 v180, v135, v136
	v_mfma_f32_32x32x16_bf16 v[2:17], v[114:117], v[182:185], v[2:17]
	ds_read_b128 v[114:117], v132 offset:61440
	v_exp_f32_e32 v132, v104
	v_exp_f32_e32 v135, v105
	v_add_f32_e32 v133, v133, v132
	v_add_f32_e32 v134, v134, v135
	v_cvt_pk_bf16_f32 v181, v132, v135
	s_waitcnt lgkmcnt(2)
	v_mfma_f32_32x32x16_bf16 v[34:49], v[126:129], v[190:193], v[34:49]
	v_exp_f32_e32 v126, v106
	v_exp_f32_e32 v127, v107
	v_add_f32_e32 v128, v133, v126
	v_add_f32_e32 v129, v134, v127
	v_cvt_pk_bf16_f32 v186, v126, v127
	v_mfma_f32_32x32x16_bf16 v[50:65], v[122:125], v[190:193], v[50:65]
	v_exp_f32_e32 v124, v108
	v_exp_f32_e32 v125, v109
	v_add_f32_e32 v122, v128, v124
	v_add_f32_e32 v123, v129, v125
	s_add_i32 m0, s101, 0xe000
	s_cmp_eq_u64 s[88:89], 0
	v_cvt_pk_bf16_f32 v187, v124, v125
	s_cbranch_scc1 .LBB0_236
	global_load_lds_dwordx4 v216, s[52:53]
.LBB0_236:
	s_waitcnt lgkmcnt(0)
	v_mfma_f32_32x32x16_bf16 v[18:33], v[118:121], v[190:193], v[18:33]
	v_exp_f32_e32 v118, v110
	v_exp_f32_e32 v119, v111
	v_add_f32_e32 v120, v122, v118
	v_add_f32_e32 v121, v123, v119
	v_cvt_pk_bf16_f32 v188, v118, v119
	v_mfma_f32_32x32x16_bf16 v[2:17], v[114:117], v[190:193], v[2:17]
	v_exp_f32_e32 v114, v112
	v_exp_f32_e32 v115, v113
	v_add_f32_e32 v116, v120, v114
	v_add_f32_e32 v117, v121, v115
	v_cvt_pk_bf16_f32 v189, v114, v115
	v_add_f32_e32 v212, v116, v117
	v_cmp_nge_f32_e32 vcc, s7, v212
	s_cbranch_vccnz .Lrare_u1o

.Lhd_u1e:
	s_add_i32 s22, s23, 2
	s_cmp_ge_u32 s22, s17
	s_cbranch_scc1 .LBB0_171
	s_lshl_b32 s26, s48, 14
	s_add_i32 s26, s11, s26
	s_add_i32 s27, s26, 0x2000
	s_mov_b32 m0, s26
	s_nop 0
	global_load_lds_dwordx4 v214, s[80:81]
	s_mov_b32 m0, s27
	s_nop 0
	global_load_lds_dwordx4 v214, s[62:63]
.LBB0_171:
	s_andn2_b64 vcc, exec, s[88:89]
	s_cbranch_vccnz .LBB0_173
	s_lshl_b32 s26, s31, 14
	s_add_i32 s26, s11, s26
	s_add_i32 m0, s26, 0xc000
	s_add_i32 s26, s26, 0xe000
	global_load_lds_dwordx4 v216, s[96:97]
	s_mov_b32 m0, s26
	s_nop 0
	global_load_lds_dwordx4 v216, s[58:59]

.Lpvo_u1e:
	s_mov_b64 s[26:27], -1
	ds_read_b128 v[98:101], v249 offset:49152
	ds_read_b128 v[114:117], v249 offset:53248
	ds_read_b128 v[130:133], v249 offset:57344
	ds_read_b128 v[194:197], v249 offset:61440
	s_waitcnt lgkmcnt(0)
	v_mfma_f32_32x32x16_bf16 v[82:97], v[98:101], v[162:165], v[34:49]
	ds_read_b128 v[206:209], v212 offset:49152
	v_mfma_f32_32x32x16_bf16 v[98:113], v[114:117], v[162:165], v[50:65]
	ds_read_b128 v[198:201], v212 offset:53248
	s_add_i32 s22, s23, 2
	s_cmp_lt_u32 s22, s17
	s_cselect_b64 s[26:27], -1, 0
	s_cmp_ge_u32 s22, s17
	s_cbranch_scc1 .LBB0_178
	s_lshl_b32 s40, s48, 14
	s_add_i32 m0, s11, s40
	s_nop 0
	global_load_lds_dwordx4 v214, s[80:81]
.LBB0_178:
	v_mfma_f32_32x32x16_bf16 v[114:129], v[130:133], v[162:165], v[18:33]
	ds_read_b128 v[202:205], v212 offset:57344
	v_mfma_f32_32x32x16_bf16 v[130:145], v[194:197], v[162:165], v[2:17]
	ds_read_b128 v[194:197], v212 offset:61440
	s_waitcnt lgkmcnt(0)
	v_mfma_f32_32x32x16_bf16 v[82:97], v[206:209], v[170:173], v[82:97]
	v_add_u32_e32 v250, s54, v246
	ds_read_b128 v[206:209], v250 offset:49152
	v_mfma_f32_32x32x16_bf16 v[98:113], v[198:201], v[170:173], v[98:113]
	ds_read_b128 v[198:201], v250 offset:53248
	s_andn2_b64 vcc, exec, s[26:27]
	s_cbranch_vccnz .LBB0_180
	s_lshl_b32 s26, s48, 14
	s_add_i32 s26, s11, s26
	s_add_i32 m0, s26, 0x2000
	s_nop 0
	global_load_lds_dwordx4 v214, s[62:63]
.LBB0_180:
	v_mfma_f32_32x32x16_bf16 v[114:129], v[202:205], v[170:173], v[114:129]
	ds_read_b128 v[202:205], v250 offset:57344
	v_mfma_f32_32x32x16_bf16 v[130:145], v[194:197], v[170:173], v[130:145]
	ds_read_b128 v[194:197], v250 offset:61440
	s_waitcnt lgkmcnt(0)
	v_mfma_f32_32x32x16_bf16 v[82:97], v[206:209], v[178:181], v[82:97]
	v_add_u32_e32 v250, s54, v247
	ds_read_b128 v[206:209], v250 offset:49152
	v_mfma_f32_32x32x16_bf16 v[98:113], v[198:201], v[178:181], v[98:113]
	ds_read_b128 v[198:201], v250 offset:53248
	v_cndmask_b32_e64 v224, 0, 1, s[88:89]
	v_cmp_ne_u32_e64 s[40:41], 1, v224
	s_andn2_b64 vcc, exec, s[88:89]
	s_cbranch_vccnz .LBB0_182
	s_lshl_b32 s26, s31, 14
	s_add_i32 s26, s11, s26
	s_add_i32 m0, s26, 0xc000
	s_nop 0
	global_load_lds_dwordx4 v216, s[96:97]
.LBB0_182:
	v_mfma_f32_32x32x16_bf16 v[114:129], v[202:205], v[178:181], v[114:129]
	ds_read_b128 v[202:205], v250 offset:57344
	v_mfma_f32_32x32x16_bf16 v[130:145], v[194:197], v[178:181], v[130:145]
	ds_read_b128 v[194:197], v250 offset:61440
	s_waitcnt lgkmcnt(0)
	v_mfma_f32_32x32x16_bf16 v[82:97], v[206:209], v[186:189], v[82:97]
	v_mfma_f32_32x32x16_bf16 v[98:113], v[198:201], v[186:189], v[98:113]
	s_and_b64 vcc, exec, s[40:41]
	s_cbranch_vccnz .LBB0_184
	s_lshl_b32 s26, s31, 14
	s_add_i32 s26, s11, s26
	s_add_i32 m0, s26, 0xe000
	s_nop 0
	global_load_lds_dwordx4 v216, s[58:59]

.Lhd_u1o:
	s_add_i32 s26, s23, 3
	s_cmp_gt_u32 s26, s16
	s_cbranch_scc1 .LBB0_211
	s_lshl_b32 s26, s48, 14
	s_add_i32 s26, s11, s26
	s_add_i32 s27, s26, 0x2000
	s_mov_b32 m0, s26
	s_nop 0
	global_load_lds_dwordx4 v214, s[50:51]
	s_mov_b32 m0, s27
	s_nop 0
	global_load_lds_dwordx4 v214, s[4:5]
.LBB0_211:
	s_andn2_b64 vcc, exec, s[88:89]
	s_cbranch_vccnz .LBB0_213
	s_lshl_b32 s26, s31, 14
	s_add_i32 s26, s11, s26
	s_add_i32 m0, s26, 0xc000
	s_add_i32 s26, s26, 0xe000
	global_load_lds_dwordx4 v216, s[0:1]
	s_mov_b32 m0, s26
	s_nop 0
	global_load_lds_dwordx4 v216, s[52:53]

.Lpvo_u1o:
	s_mov_b64 s[26:27], -1
	ds_read_b128 v[98:101], v249 offset:49152
	ds_read_b128 v[114:117], v249 offset:53248
	ds_read_b128 v[130:133], v249 offset:57344
	ds_read_b128 v[194:197], v249 offset:61440
	s_waitcnt lgkmcnt(0)
	v_mfma_f32_32x32x16_bf16 v[82:97], v[98:101], v[166:169], v[34:49]
	ds_read_b128 v[206:209], v212 offset:49152
	v_mfma_f32_32x32x16_bf16 v[98:113], v[114:117], v[166:169], v[50:65]
	ds_read_b128 v[198:201], v212 offset:53248
	s_add_i32 s40, s23, 3
	s_cmp_le_u32 s40, s16
	s_cselect_b64 s[26:27], -1, 0
	s_cmp_gt_u32 s40, s16
	s_cbranch_scc1 .LBB0_218
	s_lshl_b32 s40, s48, 14
	s_add_i32 m0, s11, s40
	s_nop 0
	global_load_lds_dwordx4 v214, s[50:51]
.LBB0_218:
	v_mfma_f32_32x32x16_bf16 v[114:129], v[130:133], v[166:169], v[18:33]
	ds_read_b128 v[202:205], v212 offset:57344
	v_mfma_f32_32x32x16_bf16 v[130:145], v[194:197], v[166:169], v[2:17]
	ds_read_b128 v[194:197], v212 offset:61440
	s_waitcnt lgkmcnt(0)
	v_mfma_f32_32x32x16_bf16 v[82:97], v[206:209], v[174:177], v[82:97]
	v_add_u32_e32 v250, s54, v246
	ds_read_b128 v[206:209], v250 offset:49152
	v_mfma_f32_32x32x16_bf16 v[98:113], v[198:201], v[174:177], v[98:113]
	ds_read_b128 v[198:201], v250 offset:53248
	s_andn2_b64 vcc, exec, s[26:27]
	s_cbranch_vccnz .LBB0_220
	s_lshl_b32 s26, s48, 14
	s_add_i32 s26, s11, s26
	s_add_i32 m0, s26, 0x2000
	s_nop 0
	global_load_lds_dwordx4 v214, s[4:5]
.LBB0_220:
	v_mfma_f32_32x32x16_bf16 v[114:129], v[202:205], v[174:177], v[114:129]
	ds_read_b128 v[202:205], v250 offset:57344
	v_mfma_f32_32x32x16_bf16 v[130:145], v[194:197], v[174:177], v[130:145]
	ds_read_b128 v[194:197], v250 offset:61440
	s_waitcnt lgkmcnt(0)
	v_mfma_f32_32x32x16_bf16 v[82:97], v[206:209], v[182:185], v[82:97]
	v_add_u32_e32 v250, s54, v247
	ds_read_b128 v[206:209], v250 offset:49152
	v_mfma_f32_32x32x16_bf16 v[98:113], v[198:201], v[182:185], v[98:113]
	ds_read_b128 v[198:201], v250 offset:53248
	v_cndmask_b32_e64 v224, 0, 1, s[88:89]
	v_cmp_ne_u32_e64 s[40:41], 1, v224
	s_andn2_b64 vcc, exec, s[88:89]
	s_cbranch_vccnz .LBB0_222
	s_lshl_b32 s26, s31, 14
	s_add_i32 s26, s11, s26
	s_add_i32 m0, s26, 0xc000
	s_nop 0
	global_load_lds_dwordx4 v216, s[0:1]
.LBB0_222:
	v_mfma_f32_32x32x16_bf16 v[114:129], v[202:205], v[182:185], v[114:129]
	ds_read_b128 v[202:205], v250 offset:57344
	v_mfma_f32_32x32x16_bf16 v[130:145], v[194:197], v[182:185], v[130:145]
	ds_read_b128 v[194:197], v250 offset:61440
	s_waitcnt lgkmcnt(0)
	v_mfma_f32_32x32x16_bf16 v[82:97], v[206:209], v[190:193], v[82:97]
	v_mfma_f32_32x32x16_bf16 v[98:113], v[198:201], v[190:193], v[98:113]
	s_and_b64 vcc, exec, s[40:41]
	s_cbranch_vccnz .LBB0_224
	s_lshl_b32 s26, s31, 14
	s_add_i32 s26, s11, s26
	s_add_i32 m0, s26, 0xe000
	s_nop 0
	global_load_lds_dwordx4 v216, s[52:53]

.LBB0_288:
	s_lshl_b32 s21, s31, 14
	s_lshl_b32 s100, s28, 14
	s_add_i32 s100, s10, s100
	s_lshl_b32 s101, s23, 14
	s_add_i32 s101, s10, s101
	ds_read_b128 v[126:129], v212 offset:49152
	s_waitcnt lgkmcnt(1)
	v_mfma_f32_32x32x16_bf16 v[82:97], v[98:101], v[146:149], v[66:81]
	ds_read_b128 v[122:125], v102 offset:8192
	v_mfma_f32_32x32x16_bf16 v[98:113], v[114:117], v[146:149], v[66:81]
	v_add_u32_e32 v139, s21, v241
	ds_read_b128 v[114:117], v139
	v_mfma_f32_32x32x16_bf16 v[82:97], v[118:121], v[150:153], v[82:97]
	ds_read_b128 v[118:121], v139 offset:8192
	s_waitcnt lgkmcnt(0)
	v_mfma_f32_32x32x16_bf16 v[98:113], v[122:125], v[150:153], v[98:113]
	v_add_u32_e32 v139, s21, v242
	ds_read_b128 v[122:125], v139
	v_mfma_f32_32x32x16_bf16 v[82:97], v[114:117], v[154:157], v[82:97]
	ds_read_b128 v[114:117], v139 offset:8192
	v_mfma_f32_32x32x16_bf16 v[98:113], v[118:121], v[154:157], v[98:113]
	s_waitcnt lgkmcnt(0)
	v_mfma_f32_32x32x16_bf16 v[82:97], v[122:125], v[158:161], v[82:97]
	v_mfma_f32_32x32x16_bf16 v[98:113], v[114:117], v[158:161], v[98:113]
	s_nop 0
	ds_read_b128 v[122:125], v212 offset:53248
	ds_read_b128 v[118:121], v212 offset:57344
	ds_read_b128 v[114:117], v212 offset:61440
	s_cmp_le_u32 s20, s16
	s_cbranch_scc0 .Lnear_u2e
.LBB0_291:
	v_mfma_f32_32x32x16_bf16 v[50:65], v[126:129], v[162:165], v[50:65]
	ds_read_b128 v[126:129], v0 offset:49152
	s_nop 1
	v_exp_f32_e32 v130, v82
	v_exp_f32_e32 v131, v83
	v_add_f32_e32 v132, v1, v130
	v_add_f32_e32 v133, v1, v131
	v_cvt_pk_bf16_f32 v166, v130, v131
	s_waitcnt lgkmcnt(3)
	v_mfma_f32_32x32x16_bf16 v[34:49], v[122:125], v[162:165], v[34:49]
	ds_read_b128 v[122:125], v0 offset:53248
	v_exp_f32_e32 v134, v84
	v_exp_f32_e32 v135, v85
	s_add_i32 s21, s22, 2
	v_add_f32_e32 v130, v132, v134
	v_add_f32_e32 v131, v133, v135
	v_cvt_pk_bf16_f32 v167, v134, v135
	s_mov_b32 m0, s100
	s_cmp_ge_u32 s21, s18
	s_cbranch_scc1 .LBB0_293
	global_load_lds_dwordx4 v214, s[80:81]
.LBB0_293:
	s_waitcnt lgkmcnt(2)
	v_mfma_f32_32x32x16_bf16 v[18:33], v[118:121], v[162:165], v[18:33]
	ds_read_b128 v[118:121], v0 offset:57344
	v_exp_f32_e32 v132, v86
	v_exp_f32_e32 v133, v87
	v_add_f32_e32 v130, v130, v132
	v_add_f32_e32 v131, v131, v133
	v_cvt_pk_bf16_f32 v168, v132, v133
	v_mfma_f32_32x32x16_bf16 v[2:17], v[114:117], v[162:165], v[2:17]
	ds_read_b128 v[114:117], v0 offset:61440
	v_exp_f32_e32 v0, v88
	v_exp_f32_e32 v132, v89
	v_add_f32_e32 v130, v130, v0
	v_add_f32_e32 v131, v131, v132
	v_cvt_pk_bf16_f32 v169, v0, v132
	s_waitcnt lgkmcnt(2)
	v_mfma_f32_32x32x16_bf16 v[50:65], v[126:129], v[170:173], v[50:65]
	v_add_u32_e32 v0, s36, v247
	ds_read_b128 v[126:129], v0 offset:49152
	v_exp_f32_e32 v132, v90
	v_exp_f32_e32 v133, v91
	v_add_f32_e32 v130, v130, v132
	v_add_f32_e32 v131, v131, v133
	v_cvt_pk_bf16_f32 v174, v132, v133
	v_mfma_f32_32x32x16_bf16 v[34:49], v[122:125], v[170:173], v[34:49]
	ds_read_b128 v[122:125], v0 offset:53248
	v_exp_f32_e32 v132, v92
	v_exp_f32_e32 v133, v93
	v_add_f32_e32 v130, v130, v132
	v_add_f32_e32 v131, v131, v133
	s_add_i32 m0, s100, 0x2000
	s_cmp_ge_u32 s21, s18
	v_cvt_pk_bf16_f32 v175, v132, v133
	s_cbranch_scc1 .LBB0_295
	global_load_lds_dwordx4 v214, s[62:63]
.LBB0_295:
	s_waitcnt lgkmcnt(2)
	v_mfma_f32_32x32x16_bf16 v[18:33], v[118:121], v[170:173], v[18:33]
	ds_read_b128 v[118:121], v0 offset:57344
	v_exp_f32_e32 v132, v94
	v_exp_f32_e32 v133, v95
	v_add_f32_e32 v130, v130, v132
	v_add_f32_e32 v131, v131, v133
	v_cvt_pk_bf16_f32 v176, v132, v133
	v_mfma_f32_32x32x16_bf16 v[2:17], v[114:117], v[170:173], v[2:17]
	ds_read_b128 v[114:117], v0 offset:61440
	v_exp_f32_e32 v0, v96
	v_exp_f32_e32 v132, v97
	v_add_f32_e32 v130, v130, v0
	v_add_f32_e32 v131, v131, v132
	v_cvt_pk_bf16_f32 v177, v0, v132
	s_waitcnt lgkmcnt(2)
	v_mfma_f32_32x32x16_bf16 v[50:65], v[126:129], v[178:181], v[50:65]
	v_add_u32_e32 v0, s36, v248
	ds_read_b128 v[126:129], v0 offset:49152
	v_exp_f32_e32 v132, v98
	v_exp_f32_e32 v133, v99
	v_add_f32_e32 v130, v130, v132
	v_add_f32_e32 v131, v131, v133
	v_cvt_pk_bf16_f32 v182, v132, v133
	v_mfma_f32_32x32x16_bf16 v[34:49], v[122:125], v[178:181], v[34:49]
	v_exp_f32_e32 v132, v100
	v_exp_f32_e32 v133, v101
	ds_read_b128 v[122:125], v0 offset:53248
	v_add_f32_e32 v130, v130, v132
	v_add_f32_e32 v131, v131, v133
	v_cvt_pk_bf16_f32 v183, v132, v133
	s_add_i32 m0, s101, 0xc000
	s_cmp_eq_u64 s[44:45], 0
	s_cbranch_scc1 .LBB0_297
	global_load_lds_dwordx4 v216, s[96:97]
.LBB0_297:
	s_waitcnt lgkmcnt(2)
	v_mfma_f32_32x32x16_bf16 v[18:33], v[118:121], v[178:181], v[18:33]
	ds_read_b128 v[118:121], v0 offset:57344
	v_exp_f32_e32 v132, v102
	v_exp_f32_e32 v133, v103
	v_add_f32_e32 v130, v130, v132
	v_add_f32_e32 v131, v131, v133
	v_cvt_pk_bf16_f32 v184, v132, v133
	v_mfma_f32_32x32x16_bf16 v[2:17], v[114:117], v[178:181], v[2:17]
	ds_read_b128 v[114:117], v0 offset:61440
	v_exp_f32_e32 v0, v104
	v_exp_f32_e32 v132, v105
	v_add_f32_e32 v130, v130, v0
	v_add_f32_e32 v131, v131, v132
	v_cvt_pk_bf16_f32 v185, v0, v132
	s_waitcnt lgkmcnt(2)
	v_mfma_f32_32x32x16_bf16 v[50:65], v[126:129], v[186:189], v[50:65]
	v_exp_f32_e32 v0, v106
	v_exp_f32_e32 v126, v107
	v_add_f32_e32 v127, v130, v0
	v_add_f32_e32 v128, v131, v126
	v_cvt_pk_bf16_f32 v190, v0, v126
	v_mfma_f32_32x32x16_bf16 v[34:49], v[122:125], v[186:189], v[34:49]
	v_exp_f32_e32 v123, v108
	v_exp_f32_e32 v124, v109
	v_add_f32_e32 v0, v127, v123
	v_add_f32_e32 v122, v128, v124
	s_add_i32 m0, s101, 0xe000
	s_cmp_eq_u64 s[44:45], 0
	v_cvt_pk_bf16_f32 v191, v123, v124
	s_cbranch_scc1 .LBB0_299
	global_load_lds_dwordx4 v216, s[58:59]
.LBB0_299:
	s_waitcnt lgkmcnt(0)
	v_mfma_f32_32x32x16_bf16 v[18:33], v[118:121], v[186:189], v[18:33]
	v_exp_f32_e32 v118, v110
	v_exp_f32_e32 v119, v111
	v_add_f32_e32 v0, v0, v118
	v_add_f32_e32 v120, v122, v119
	v_cvt_pk_bf16_f32 v192, v118, v119
	v_mfma_f32_32x32x16_bf16 v[2:17], v[114:117], v[186:189], v[2:17]
	v_exp_f32_e32 v114, v112
	v_exp_f32_e32 v115, v113
	v_add_f32_e32 v0, v0, v114
	v_add_f32_e32 v116, v120, v115
	v_cvt_pk_bf16_f32 v193, v114, v115
	v_add_f32_e32 v212, v0, v116
	v_cmp_nge_f32_e32 vcc, s7, v212
	s_cbranch_vccnz .Lrare_u2e

.LBB0_328:
	s_lshl_b32 s26, s31, 14
	s_lshl_b32 s100, s28, 14
	s_add_i32 s100, s10, s100
	s_lshl_b32 s101, s23, 14
	s_add_i32 s101, s10, s101
	ds_read_b128 v[126:129], v212 offset:49152
	s_waitcnt lgkmcnt(1)
	v_mfma_f32_32x32x16_bf16 v[82:97], v[98:101], v[146:149], v[66:81]
	ds_read_b128 v[122:125], v102 offset:8192
	v_mfma_f32_32x32x16_bf16 v[98:113], v[114:117], v[146:149], v[66:81]
	v_add_u32_e32 v139, s26, v241
	ds_read_b128 v[114:117], v139
	v_mfma_f32_32x32x16_bf16 v[82:97], v[118:121], v[150:153], v[82:97]
	ds_read_b128 v[118:121], v139 offset:8192
	s_waitcnt lgkmcnt(0)
	v_mfma_f32_32x32x16_bf16 v[98:113], v[122:125], v[150:153], v[98:113]
	v_add_u32_e32 v139, s26, v242
	ds_read_b128 v[122:125], v139
	v_mfma_f32_32x32x16_bf16 v[82:97], v[114:117], v[154:157], v[82:97]
	ds_read_b128 v[114:117], v139 offset:8192
	v_mfma_f32_32x32x16_bf16 v[98:113], v[118:121], v[154:157], v[98:113]
	s_waitcnt lgkmcnt(0)
	v_mfma_f32_32x32x16_bf16 v[82:97], v[122:125], v[158:161], v[82:97]
	v_mfma_f32_32x32x16_bf16 v[98:113], v[114:117], v[158:161], v[98:113]
	s_nop 0
	ds_read_b128 v[122:125], v212 offset:53248
	ds_read_b128 v[118:121], v212 offset:57344
	ds_read_b128 v[114:117], v212 offset:61440
	s_add_i32 s26, s20, 64
	s_cmp_le_u32 s26, s16
	s_cbranch_scc0 .Lnear_u2o
.LBB0_331:
	v_mfma_f32_32x32x16_bf16 v[50:65], v[126:129], v[166:169], v[50:65]
	ds_read_b128 v[126:129], v0 offset:49152
	s_nop 0
	v_exp_f32_e32 v130, v82
	v_exp_f32_e32 v131, v83
	v_add_f32_e32 v132, v1, v130
	v_add_f32_e32 v133, v1, v131
	v_cvt_pk_bf16_f32 v162, v130, v131
	s_waitcnt lgkmcnt(3)
	v_mfma_f32_32x32x16_bf16 v[34:49], v[122:125], v[166:169], v[34:49]
	ds_read_b128 v[122:125], v0 offset:53248
	v_exp_f32_e32 v130, v84
	v_exp_f32_e32 v131, v85
	s_add_i32 s22, s22, 3
	s_cmp_le_u32 s22, s17
	v_add_f32_e32 v132, v132, v130
	v_add_f32_e32 v133, v133, v131
	v_cvt_pk_bf16_f32 v163, v130, v131
	s_cselect_b64 s[26:27], -1, 0
	s_mov_b32 m0, s100
	s_cmp_gt_u32 s22, s17
	s_cbranch_scc1 .LBB0_333
	global_load_lds_dwordx4 v214, s[50:51]
.LBB0_333:
	s_waitcnt lgkmcnt(2)
	v_mfma_f32_32x32x16_bf16 v[18:33], v[118:121], v[166:169], v[18:33]
	ds_read_b128 v[118:121], v0 offset:57344
	v_exp_f32_e32 v134, v86
	v_exp_f32_e32 v135, v87
	v_add_f32_e32 v132, v132, v134
	v_add_f32_e32 v133, v133, v135
	v_cvt_pk_bf16_f32 v164, v134, v135
	v_mfma_f32_32x32x16_bf16 v[2:17], v[114:117], v[166:169], v[2:17]
	ds_read_b128 v[114:117], v0 offset:61440
	v_exp_f32_e32 v0, v88
	v_exp_f32_e32 v134, v89
	v_add_f32_e32 v132, v132, v0
	v_add_f32_e32 v133, v133, v134
	v_cvt_pk_bf16_f32 v165, v0, v134
	s_waitcnt lgkmcnt(2)
	v_mfma_f32_32x32x16_bf16 v[50:65], v[126:129], v[174:177], v[50:65]
	v_add_u32_e32 v0, s36, v247
	ds_read_b128 v[126:129], v0 offset:49152
	v_exp_f32_e32 v134, v90
	v_exp_f32_e32 v135, v91
	v_add_f32_e32 v132, v132, v134
	v_add_f32_e32 v133, v133, v135
	v_cvt_pk_bf16_f32 v170, v134, v135
	v_mfma_f32_32x32x16_bf16 v[34:49], v[122:125], v[174:177], v[34:49]
	ds_read_b128 v[122:125], v0 offset:53248
	v_exp_f32_e32 v134, v92
	v_exp_f32_e32 v135, v93
	v_add_f32_e32 v132, v132, v134
	v_add_f32_e32 v133, v133, v135
	s_add_i32 m0, s100, 0x2000
	s_andn2_b64 vcc, exec, s[26:27]
	v_cvt_pk_bf16_f32 v171, v134, v135
	s_cbranch_vccnz .LBB0_335
	global_load_lds_dwordx4 v214, s[4:5]
.LBB0_335:
	s_waitcnt lgkmcnt(2)
	v_mfma_f32_32x32x16_bf16 v[18:33], v[118:121], v[174:177], v[18:33]
	ds_read_b128 v[118:121], v0 offset:57344
	v_exp_f32_e32 v130, v94
	v_exp_f32_e32 v131, v95
	v_add_f32_e32 v132, v132, v130
	v_add_f32_e32 v133, v133, v131
	v_cvt_pk_bf16_f32 v172, v130, v131
	v_mfma_f32_32x32x16_bf16 v[2:17], v[114:117], v[174:177], v[2:17]
	ds_read_b128 v[114:117], v0 offset:61440
	v_exp_f32_e32 v0, v96
	v_exp_f32_e32 v130, v97
	v_add_f32_e32 v131, v132, v0
	v_add_f32_e32 v132, v133, v130
	v_cvt_pk_bf16_f32 v173, v0, v130
	s_waitcnt lgkmcnt(2)
	v_mfma_f32_32x32x16_bf16 v[50:65], v[126:129], v[182:185], v[50:65]
	v_add_u32_e32 v0, s36, v248
	ds_read_b128 v[126:129], v0 offset:49152
	v_exp_f32_e32 v130, v98
	v_exp_f32_e32 v133, v99
	v_add_f32_e32 v131, v131, v130
	v_add_f32_e32 v134, v132, v133
	v_cvt_pk_bf16_f32 v178, v130, v133
	v_mfma_f32_32x32x16_bf16 v[34:49], v[122:125], v[182:185], v[34:49]
	v_exp_f32_e32 v130, v100
	v_exp_f32_e32 v135, v101
	ds_read_b128 v[122:125], v0 offset:53248
	v_add_f32_e32 v132, v131, v130
	v_add_f32_e32 v133, v134, v135
	v_cvt_pk_bf16_f32 v179, v130, v135
	s_add_i32 m0, s101, 0xc000
	s_cmp_eq_u64 s[44:45], 0
	s_cbranch_scc1 .LBB0_337
	global_load_lds_dwordx4 v216, s[0:1]
.LBB0_337:
	s_waitcnt lgkmcnt(2)
	v_mfma_f32_32x32x16_bf16 v[18:33], v[118:121], v[182:185], v[18:33]
	ds_read_b128 v[118:121], v0 offset:57344
	v_exp_f32_e32 v134, v102
	v_exp_f32_e32 v135, v103
	v_add_f32_e32 v132, v132, v134
	v_add_f32_e32 v133, v133, v135
	v_cvt_pk_bf16_f32 v180, v134, v135
	v_mfma_f32_32x32x16_bf16 v[2:17], v[114:117], v[182:185], v[2:17]
	ds_read_b128 v[114:117], v0 offset:61440
	v_exp_f32_e32 v0, v104
	v_exp_f32_e32 v134, v105
	v_add_f32_e32 v132, v132, v0
	v_add_f32_e32 v133, v133, v134
	v_cvt_pk_bf16_f32 v181, v0, v134
	s_waitcnt lgkmcnt(2)
	v_mfma_f32_32x32x16_bf16 v[50:65], v[126:129], v[190:193], v[50:65]
	v_exp_f32_e32 v0, v106
	v_exp_f32_e32 v126, v107
	v_add_f32_e32 v127, v132, v0
	v_add_f32_e32 v128, v133, v126
	v_cvt_pk_bf16_f32 v186, v0, v126
	v_mfma_f32_32x32x16_bf16 v[34:49], v[122:125], v[190:193], v[34:49]
	v_exp_f32_e32 v123, v108
	v_exp_f32_e32 v124, v109
	v_add_f32_e32 v0, v127, v123
	v_add_f32_e32 v122, v128, v124
	s_add_i32 m0, s101, 0xe000
	s_cmp_eq_u64 s[44:45], 0
	v_cvt_pk_bf16_f32 v187, v123, v124
	s_cbranch_scc1 .LBB0_339
	global_load_lds_dwordx4 v216, s[52:53]
.LBB0_339:
	s_waitcnt lgkmcnt(0)
	v_mfma_f32_32x32x16_bf16 v[18:33], v[118:121], v[190:193], v[18:33]
	v_exp_f32_e32 v118, v110
	v_exp_f32_e32 v119, v111
	v_add_f32_e32 v0, v0, v118
	v_add_f32_e32 v120, v122, v119
	v_cvt_pk_bf16_f32 v188, v118, v119
	v_mfma_f32_32x32x16_bf16 v[2:17], v[114:117], v[190:193], v[2:17]
	v_exp_f32_e32 v114, v112
	v_exp_f32_e32 v115, v113
	v_add_f32_e32 v0, v0, v114
	v_add_f32_e32 v116, v120, v115
	v_cvt_pk_bf16_f32 v189, v114, v115
	v_add_f32_e32 v212, v0, v116
	v_cmp_nge_f32_e32 vcc, s7, v212
	s_cbranch_vccnz .Lrare_u2o

.Lhd_u2e:
	s_add_i32 s21, s22, 2
	s_cmp_ge_u32 s21, s18
	s_cbranch_scc1 .LBB0_274
	s_lshl_b32 s26, s28, 14
	s_add_i32 s26, s10, s26
	s_add_i32 s27, s26, 0x2000
	s_mov_b32 m0, s26
	s_nop 0
	global_load_lds_dwordx4 v214, s[80:81]
	s_mov_b32 m0, s27
	s_nop 0
	global_load_lds_dwordx4 v214, s[62:63]
.LBB0_274:
	s_andn2_b64 vcc, exec, s[44:45]
	s_cbranch_vccnz .LBB0_276
	s_lshl_b32 s26, s23, 14
	s_add_i32 s26, s10, s26
	s_add_i32 m0, s26, 0xc000
	s_add_i32 s26, s26, 0xe000
	global_load_lds_dwordx4 v216, s[96:97]
	s_mov_b32 m0, s26
	s_nop 0
	global_load_lds_dwordx4 v216, s[58:59]

.Lpvo_u2e:
	s_mov_b64 s[26:27], -1
	ds_read_b128 v[98:101], v212 offset:49152
	ds_read_b128 v[114:117], v212 offset:53248
	ds_read_b128 v[130:133], v212 offset:57344
	ds_read_b128 v[194:197], v212 offset:61440
	s_waitcnt lgkmcnt(0)
	v_mfma_f32_32x32x16_bf16 v[82:97], v[98:101], v[162:165], v[50:65]
	ds_read_b128 v[206:209], v0 offset:49152
	v_mfma_f32_32x32x16_bf16 v[98:113], v[114:117], v[162:165], v[34:49]
	ds_read_b128 v[198:201], v0 offset:53248
	s_add_i32 s21, s22, 2
	s_cmp_lt_u32 s21, s18
	s_cselect_b64 s[26:27], -1, 0
	s_cmp_ge_u32 s21, s18
	s_cbranch_scc1 .LBB0_281
	s_lshl_b32 s37, s28, 14
	s_add_i32 m0, s10, s37
	s_nop 0
	global_load_lds_dwordx4 v214, s[80:81]
.LBB0_281:
	v_mfma_f32_32x32x16_bf16 v[114:129], v[130:133], v[162:165], v[18:33]
	ds_read_b128 v[202:205], v0 offset:57344
	v_mfma_f32_32x32x16_bf16 v[130:145], v[194:197], v[162:165], v[2:17]
	ds_read_b128 v[194:197], v0 offset:61440
	s_waitcnt lgkmcnt(0)
	v_mfma_f32_32x32x16_bf16 v[82:97], v[206:209], v[170:173], v[82:97]
	v_add_u32_e32 v250, s36, v247
	ds_read_b128 v[206:209], v250 offset:49152
	v_mfma_f32_32x32x16_bf16 v[98:113], v[198:201], v[170:173], v[98:113]
	ds_read_b128 v[198:201], v250 offset:53248
	s_andn2_b64 vcc, exec, s[26:27]
	s_cbranch_vccnz .LBB0_283
	s_lshl_b32 s26, s28, 14
	s_add_i32 s26, s10, s26
	s_add_i32 m0, s26, 0x2000
	s_nop 0
	global_load_lds_dwordx4 v214, s[62:63]
.LBB0_283:
	v_mfma_f32_32x32x16_bf16 v[114:129], v[202:205], v[170:173], v[114:129]
	ds_read_b128 v[202:205], v250 offset:57344
	v_mfma_f32_32x32x16_bf16 v[130:145], v[194:197], v[170:173], v[130:145]
	ds_read_b128 v[194:197], v250 offset:61440
	s_waitcnt lgkmcnt(0)
	v_mfma_f32_32x32x16_bf16 v[82:97], v[206:209], v[178:181], v[82:97]
	v_add_u32_e32 v250, s36, v248
	ds_read_b128 v[206:209], v250 offset:49152
	v_mfma_f32_32x32x16_bf16 v[98:113], v[198:201], v[178:181], v[98:113]
	ds_read_b128 v[198:201], v250 offset:53248
	v_cndmask_b32_e64 v224, 0, 1, s[44:45]
	v_cmp_ne_u32_e64 s[40:41], 1, v224
	s_andn2_b64 vcc, exec, s[44:45]
	s_cbranch_vccnz .LBB0_285
	s_lshl_b32 s26, s23, 14
	s_add_i32 s26, s10, s26
	s_add_i32 m0, s26, 0xc000
	s_nop 0
	global_load_lds_dwordx4 v216, s[96:97]
.LBB0_285:
	v_mfma_f32_32x32x16_bf16 v[114:129], v[202:205], v[178:181], v[114:129]
	ds_read_b128 v[202:205], v250 offset:57344
	v_mfma_f32_32x32x16_bf16 v[130:145], v[194:197], v[178:181], v[130:145]
	ds_read_b128 v[194:197], v250 offset:61440
	s_waitcnt lgkmcnt(0)
	v_mfma_f32_32x32x16_bf16 v[82:97], v[206:209], v[186:189], v[82:97]
	v_mfma_f32_32x32x16_bf16 v[98:113], v[198:201], v[186:189], v[98:113]
	s_and_b64 vcc, exec, s[40:41]
	s_cbranch_vccnz .LBB0_287
	s_lshl_b32 s26, s23, 14
	s_add_i32 s26, s10, s26
	s_add_i32 m0, s26, 0xe000
	s_nop 0
	global_load_lds_dwordx4 v216, s[58:59]

.Lhd_u2o:
	s_add_i32 s26, s22, 3
	s_cmp_gt_u32 s26, s17
	s_cbranch_scc1 .LBB0_314
	s_lshl_b32 s26, s28, 14
	s_add_i32 s26, s10, s26
	s_add_i32 s27, s26, 0x2000
	s_mov_b32 m0, s26
	s_nop 0
	global_load_lds_dwordx4 v214, s[50:51]
	s_mov_b32 m0, s27
	s_nop 0
	global_load_lds_dwordx4 v214, s[4:5]
.LBB0_314:
	s_andn2_b64 vcc, exec, s[44:45]
	s_cbranch_vccnz .LBB0_316
	s_lshl_b32 s26, s23, 14
	s_add_i32 s26, s10, s26
	s_add_i32 m0, s26, 0xc000
	s_add_i32 s26, s26, 0xe000
	global_load_lds_dwordx4 v216, s[0:1]
	s_mov_b32 m0, s26
	s_nop 0
	global_load_lds_dwordx4 v216, s[52:53]

.Lpvo_u2o:
	s_mov_b64 s[26:27], -1
	ds_read_b128 v[98:101], v212 offset:49152
	ds_read_b128 v[114:117], v212 offset:53248
	ds_read_b128 v[130:133], v212 offset:57344
	ds_read_b128 v[194:197], v212 offset:61440
	s_waitcnt lgkmcnt(0)
	v_mfma_f32_32x32x16_bf16 v[82:97], v[98:101], v[166:169], v[50:65]
	ds_read_b128 v[206:209], v0 offset:49152
	v_mfma_f32_32x32x16_bf16 v[98:113], v[114:117], v[166:169], v[34:49]
	ds_read_b128 v[198:201], v0 offset:53248
	s_add_i32 s37, s22, 3
	s_cmp_le_u32 s37, s17
	s_cselect_b64 s[26:27], -1, 0
	s_cmp_gt_u32 s37, s17
	s_cbranch_scc1 .LBB0_321
	s_lshl_b32 s37, s28, 14
	s_add_i32 m0, s10, s37
	s_nop 0
	global_load_lds_dwordx4 v214, s[50:51]
.LBB0_321:
	v_mfma_f32_32x32x16_bf16 v[114:129], v[130:133], v[166:169], v[18:33]
	ds_read_b128 v[202:205], v0 offset:57344
	v_mfma_f32_32x32x16_bf16 v[130:145], v[194:197], v[166:169], v[2:17]
	ds_read_b128 v[194:197], v0 offset:61440
	s_waitcnt lgkmcnt(0)
	v_mfma_f32_32x32x16_bf16 v[82:97], v[206:209], v[174:177], v[82:97]
	v_add_u32_e32 v250, s36, v247
	ds_read_b128 v[206:209], v250 offset:49152
	v_mfma_f32_32x32x16_bf16 v[98:113], v[198:201], v[174:177], v[98:113]
	ds_read_b128 v[198:201], v250 offset:53248
	s_andn2_b64 vcc, exec, s[26:27]
	s_cbranch_vccnz .LBB0_323
	s_lshl_b32 s26, s28, 14
	s_add_i32 s26, s10, s26
	s_add_i32 m0, s26, 0x2000
	s_nop 0
	global_load_lds_dwordx4 v214, s[4:5]
.LBB0_323:
	v_mfma_f32_32x32x16_bf16 v[114:129], v[202:205], v[174:177], v[114:129]
	ds_read_b128 v[202:205], v250 offset:57344
	v_mfma_f32_32x32x16_bf16 v[130:145], v[194:197], v[174:177], v[130:145]
	ds_read_b128 v[194:197], v250 offset:61440
	s_waitcnt lgkmcnt(0)
	v_mfma_f32_32x32x16_bf16 v[82:97], v[206:209], v[182:185], v[82:97]
	v_add_u32_e32 v250, s36, v248
	ds_read_b128 v[206:209], v250 offset:49152
	v_mfma_f32_32x32x16_bf16 v[98:113], v[198:201], v[182:185], v[98:113]
	ds_read_b128 v[198:201], v250 offset:53248
	v_cndmask_b32_e64 v224, 0, 1, s[44:45]
	v_cmp_ne_u32_e64 s[40:41], 1, v224
	s_andn2_b64 vcc, exec, s[44:45]
	s_cbranch_vccnz .LBB0_325
	s_lshl_b32 s26, s23, 14
	s_add_i32 s26, s10, s26
	s_add_i32 m0, s26, 0xc000
	s_nop 0
	global_load_lds_dwordx4 v216, s[0:1]
.LBB0_325:
	v_mfma_f32_32x32x16_bf16 v[114:129], v[202:205], v[182:185], v[114:129]
	ds_read_b128 v[202:205], v250 offset:57344
	v_mfma_f32_32x32x16_bf16 v[130:145], v[194:197], v[182:185], v[130:145]
	ds_read_b128 v[194:197], v250 offset:61440
	s_waitcnt lgkmcnt(0)
	v_mfma_f32_32x32x16_bf16 v[82:97], v[206:209], v[190:193], v[82:97]
	v_mfma_f32_32x32x16_bf16 v[98:113], v[198:201], v[190:193], v[98:113]
	s_and_b64 vcc, exec, s[40:41]
	s_cbranch_vccnz .LBB0_327
	s_lshl_b32 s26, s23, 14
	s_add_i32 s26, s10, s26
	s_add_i32 m0, s26, 0xe000
	s_nop 0
	global_load_lds_dwordx4 v216, s[52:53]
